# window loop: packed f32 fma/add/mul for exp arguments, row sums, bias add and O rescale; Q fragments read once per unit
# speedup vs baseline: 1.0086x; 1.0034x over previous
.LBB0_1258:
	s_mov_b64 s[18:19], s[4:5]
	v_mov_b64_e32 v[34:35], v[16:17]
	v_mov_b64_e32 v[36:37], v[16:17]
	v_mov_b64_e32 v[38:39], v[16:17]
	v_mov_b64_e32 v[40:41], v[16:17]
	v_mov_b64_e32 v[42:43], v[16:17]
	v_mov_b64_e32 v[44:45], v[16:17]
	v_mov_b64_e32 v[46:47], v[16:17]
	v_mov_b64_e32 v[48:49], v[16:17]
	v_mov_b64_e32 v[50:51], v[16:17]
	v_mov_b64_e32 v[52:53], v[16:17]
	v_mov_b64_e32 v[54:55], v[16:17]
	v_mov_b64_e32 v[56:57], v[16:17]
	v_mov_b64_e32 v[58:59], v[16:17]
	v_mov_b64_e32 v[60:61], v[16:17]
	v_mov_b64_e32 v[62:63], v[16:17]
	v_mov_b64_e32 v[64:65], v[16:17]
	v_mov_b32_e32 v66, 0
	v_mov_b32_e32 v242, 0x3fb8aa3b
	ds_read_b128 v[68:71], v224
	ds_read_b128 v[72:75], v224 offset:32
	ds_read_b128 v[76:79], v224 offset:64
	ds_read_b128 v[80:83], v224 offset:96
	s_waitcnt lgkmcnt(0)
.Lw_loop:
	s_add_u32 s20, s18, 0x800000
	s_addc_u32 s21, s19, 0
	global_load_dwordx4 v[130:133], v194, s[20:21]
	global_load_dwordx4 v[146:149], v200, s[20:21]
	global_load_dwordx4 v[134:137], v194, s[20:21] offset:1024
	global_load_dwordx4 v[150:153], v202, s[20:21]
	global_load_dwordx4 v[138:141], v194, s[20:21] offset:2048
	global_load_dwordx4 v[154:157], v204, s[20:21]
	global_load_dwordx4 v[142:145], v194, s[20:21] offset:3072
	global_load_dwordx4 v[158:161], v206, s[20:21]
	s_cmp_lt_i32 s17, s96
	s_cbranch_scc0 .Lw_near
	s_cmp_eq_u32 s17, s15
	s_cbranch_scc1 .Lw_band
	s_waitcnt vmcnt(8)
	v_mfma_f32_32x32x16_bf16 v[162:177], v[98:101], v[68:71], 0
	v_mfma_f32_32x32x16_bf16 v[178:193], v[114:117], v[68:71], 0
	v_mfma_f32_32x32x16_bf16 v[162:177], v[102:105], v[72:75], v[162:177]
	v_mfma_f32_32x32x16_bf16 v[178:193], v[118:121], v[72:75], v[178:193]
	v_mfma_f32_32x32x16_bf16 v[162:177], v[106:109], v[76:79], v[162:177]
	v_mfma_f32_32x32x16_bf16 v[178:193], v[122:125], v[76:79], v[178:193]
	v_mfma_f32_32x32x16_bf16 v[162:177], v[110:113], v[80:83], v[162:177]
	v_mfma_f32_32x32x16_bf16 v[178:193], v[126:129], v[80:83], v[178:193]
	s_add_u32 s22, s18, 0x2000
	s_addc_u32 s23, s19, 0
	global_load_dwordx4 v[98:101], v194, s[22:23]
	global_load_dwordx4 v[102:105], v194, s[22:23] offset:1024
	global_load_dwordx4 v[106:109], v194, s[22:23] offset:2048
	global_load_dwordx4 v[110:113], v194, s[22:23] offset:3072
	global_load_dwordx4 v[114:117], v200, s[22:23]
	global_load_dwordx4 v[118:121], v202, s[22:23]
	global_load_dwordx4 v[122:125], v204, s[22:23]
	global_load_dwordx4 v[126:129], v206, s[22:23]
	s_nop 1
	v_max3_f32 v92, v162, v163, v164
	v_max3_f32 v92, v92, v165, v166
	v_max3_f32 v92, v92, v167, v168
	v_max3_f32 v92, v92, v169, v170
	v_max3_f32 v92, v92, v171, v172
	v_max3_f32 v92, v92, v173, v174
	v_max3_f32 v92, v92, v175, v176
	v_max3_f32 v92, v92, v177, v177
	v_max3_f32 v97, v178, v179, v180
	v_max3_f32 v97, v97, v181, v182
	v_max3_f32 v97, v97, v183, v184
	v_max3_f32 v97, v97, v185, v186
	v_max3_f32 v97, v97, v187, v188
	v_max3_f32 v97, v97, v189, v190
	v_max3_f32 v97, v97, v191, v192
	v_max3_f32 v97, v97, v193, v193
	v_max_f32_e32 v92, v92, v97
	v_fmamk_f32 v92, v92, 0x3fb8aa3b, v208
	v_mov_b32_e32 v93, v92
	s_nop 1
	v_permlane32_swap_b32_e32 v92, v93
	v_max3_f32 v97, v234, v92, v93
	v_cmp_neq_f32_e32 vcc, s68, v97
	s_nop 1
	v_cndmask_b32_e32 v94, 0, v97, vcc
	v_cmp_neq_f32_e32 vcc, v97, v234
	s_cbranch_vccz .Lw_nr_far
	v_sub_f32_e32 v96, v234, v94
	v_exp_f32_e32 v96, v96
	s_nop 0
	v_pk_mul_f32 v[34:35], v[34:35], v[96:97] op_sel_hi:[1,0]
	v_pk_mul_f32 v[36:37], v[36:37], v[96:97] op_sel_hi:[1,0]
	v_pk_mul_f32 v[38:39], v[38:39], v[96:97] op_sel_hi:[1,0]
	v_pk_mul_f32 v[40:41], v[40:41], v[96:97] op_sel_hi:[1,0]
	v_pk_mul_f32 v[42:43], v[42:43], v[96:97] op_sel_hi:[1,0]
	v_pk_mul_f32 v[44:45], v[44:45], v[96:97] op_sel_hi:[1,0]
	v_pk_mul_f32 v[46:47], v[46:47], v[96:97] op_sel_hi:[1,0]
	v_pk_mul_f32 v[48:49], v[48:49], v[96:97] op_sel_hi:[1,0]
	v_pk_mul_f32 v[50:51], v[50:51], v[96:97] op_sel_hi:[1,0]
	v_pk_mul_f32 v[52:53], v[52:53], v[96:97] op_sel_hi:[1,0]
	v_pk_mul_f32 v[54:55], v[54:55], v[96:97] op_sel_hi:[1,0]
	v_pk_mul_f32 v[56:57], v[56:57], v[96:97] op_sel_hi:[1,0]
	v_pk_mul_f32 v[58:59], v[58:59], v[96:97] op_sel_hi:[1,0]
	v_pk_mul_f32 v[60:61], v[60:61], v[96:97] op_sel_hi:[1,0]
	v_pk_mul_f32 v[62:63], v[62:63], v[96:97] op_sel_hi:[1,0]
	v_pk_mul_f32 v[64:65], v[64:65], v[96:97] op_sel_hi:[1,0]
	v_mul_f32_e32 v66, v96, v66
.Lw_nr_far:
	v_mov_b32_e32 v234, v97
	v_sub_f32_e32 v240, v208, v94
	v_pk_fma_f32 v[162:163], v[162:163], v[242:243], v[240:241] op_sel_hi:[1,0,0]
	v_pk_fma_f32 v[164:165], v[164:165], v[242:243], v[240:241] op_sel_hi:[1,0,0]
	v_pk_fma_f32 v[166:167], v[166:167], v[242:243], v[240:241] op_sel_hi:[1,0,0]
	v_pk_fma_f32 v[168:169], v[168:169], v[242:243], v[240:241] op_sel_hi:[1,0,0]
	v_exp_f32_e32 v162, v162
	v_exp_f32_e32 v163, v163
	v_exp_f32_e32 v164, v164
	v_exp_f32_e32 v165, v165
	v_exp_f32_e32 v166, v166
	v_exp_f32_e32 v167, v167
	v_exp_f32_e32 v168, v168
	v_exp_f32_e32 v169, v169
	v_pk_add_f32 v[236:237], v[162:163], v[164:165]
	v_pk_add_f32 v[236:237], v[236:237], v[166:167]
	v_pk_add_f32 v[236:237], v[236:237], v[168:169]
	v_cvt_pk_bf16_f32 v84, v162, v163
	v_cvt_pk_bf16_f32 v85, v164, v165
	v_cvt_pk_bf16_f32 v86, v166, v167
	v_cvt_pk_bf16_f32 v87, v168, v169
	v_pk_fma_f32 v[170:171], v[170:171], v[242:243], v[240:241] op_sel_hi:[1,0,0]
	v_pk_fma_f32 v[172:173], v[172:173], v[242:243], v[240:241] op_sel_hi:[1,0,0]
	v_pk_fma_f32 v[174:175], v[174:175], v[242:243], v[240:241] op_sel_hi:[1,0,0]
	v_pk_fma_f32 v[176:177], v[176:177], v[242:243], v[240:241] op_sel_hi:[1,0,0]
	s_waitcnt vmcnt(8)
	v_mfma_f32_32x32x16_bf16 v[34:49], v[130:133], v[84:87], v[34:49]
	v_mfma_f32_32x32x16_bf16 v[50:65], v[146:149], v[84:87], v[50:65]
	v_exp_f32_e32 v170, v170
	v_exp_f32_e32 v171, v171
	v_exp_f32_e32 v172, v172
	v_exp_f32_e32 v173, v173
	v_exp_f32_e32 v174, v174
	v_exp_f32_e32 v175, v175
	v_exp_f32_e32 v176, v176
	v_exp_f32_e32 v177, v177
	v_pk_add_f32 v[236:237], v[236:237], v[170:171]
	v_pk_add_f32 v[236:237], v[236:237], v[172:173]
	v_pk_add_f32 v[236:237], v[236:237], v[174:175]
	v_pk_add_f32 v[236:237], v[236:237], v[176:177]
	v_cvt_pk_bf16_f32 v88, v170, v171
	v_cvt_pk_bf16_f32 v89, v172, v173
	v_cvt_pk_bf16_f32 v90, v174, v175
	v_cvt_pk_bf16_f32 v91, v176, v177
	v_pk_fma_f32 v[178:179], v[178:179], v[242:243], v[240:241] op_sel_hi:[1,0,0]
	v_pk_fma_f32 v[180:181], v[180:181], v[242:243], v[240:241] op_sel_hi:[1,0,0]
	v_pk_fma_f32 v[182:183], v[182:183], v[242:243], v[240:241] op_sel_hi:[1,0,0]
	v_pk_fma_f32 v[184:185], v[184:185], v[242:243], v[240:241] op_sel_hi:[1,0,0]
	v_mfma_f32_32x32x16_bf16 v[34:49], v[134:137], v[88:91], v[34:49]
	v_mfma_f32_32x32x16_bf16 v[50:65], v[150:153], v[88:91], v[50:65]
	v_exp_f32_e32 v178, v178
	v_exp_f32_e32 v179, v179
	v_exp_f32_e32 v180, v180
	v_exp_f32_e32 v181, v181
	v_exp_f32_e32 v182, v182
	v_exp_f32_e32 v183, v183
	v_exp_f32_e32 v184, v184
	v_exp_f32_e32 v185, v185
	v_pk_add_f32 v[236:237], v[236:237], v[178:179]
	v_pk_add_f32 v[236:237], v[236:237], v[180:181]
	v_pk_add_f32 v[236:237], v[236:237], v[182:183]
	v_pk_add_f32 v[236:237], v[236:237], v[184:185]
	v_cvt_pk_bf16_f32 v84, v178, v179
	v_cvt_pk_bf16_f32 v85, v180, v181
	v_cvt_pk_bf16_f32 v86, v182, v183
	v_cvt_pk_bf16_f32 v87, v184, v185
	v_pk_fma_f32 v[186:187], v[186:187], v[242:243], v[240:241] op_sel_hi:[1,0,0]
	v_pk_fma_f32 v[188:189], v[188:189], v[242:243], v[240:241] op_sel_hi:[1,0,0]
	v_pk_fma_f32 v[190:191], v[190:191], v[242:243], v[240:241] op_sel_hi:[1,0,0]
	v_pk_fma_f32 v[192:193], v[192:193], v[242:243], v[240:241] op_sel_hi:[1,0,0]
	v_mfma_f32_32x32x16_bf16 v[34:49], v[138:141], v[84:87], v[34:49]
	v_mfma_f32_32x32x16_bf16 v[50:65], v[154:157], v[84:87], v[50:65]
	v_exp_f32_e32 v186, v186
	v_exp_f32_e32 v187, v187
	v_exp_f32_e32 v188, v188
	v_exp_f32_e32 v189, v189
	v_exp_f32_e32 v190, v190
	v_exp_f32_e32 v191, v191
	v_exp_f32_e32 v192, v192
	v_exp_f32_e32 v193, v193
	v_pk_add_f32 v[236:237], v[236:237], v[186:187]
	v_pk_add_f32 v[236:237], v[236:237], v[188:189]
	v_pk_add_f32 v[236:237], v[236:237], v[190:191]
	v_pk_add_f32 v[236:237], v[236:237], v[192:193]
	v_cvt_pk_bf16_f32 v88, v186, v187
	v_cvt_pk_bf16_f32 v89, v188, v189
	v_cvt_pk_bf16_f32 v90, v190, v191
	v_cvt_pk_bf16_f32 v91, v192, v193
	s_nop 1
	v_mfma_f32_32x32x16_bf16 v[34:49], v[142:145], v[88:91], v[34:49]
	v_mfma_f32_32x32x16_bf16 v[50:65], v[158:161], v[88:91], v[50:65]
	v_add_f32_e32 v235, v236, v237
	v_add_f32_e32 v66, v66, v235
	s_branch .Lw_next
.Lw_band:
	s_waitcnt vmcnt(8)
	v_mfma_f32_32x32x16_bf16 v[162:177], v[98:101], v[68:71], 0
	v_mfma_f32_32x32x16_bf16 v[178:193], v[114:117], v[68:71], 0
	v_mfma_f32_32x32x16_bf16 v[162:177], v[102:105], v[72:75], v[162:177]
	v_mfma_f32_32x32x16_bf16 v[178:193], v[118:121], v[72:75], v[178:193]
	v_mfma_f32_32x32x16_bf16 v[162:177], v[106:109], v[76:79], v[162:177]
	v_mfma_f32_32x32x16_bf16 v[178:193], v[122:125], v[76:79], v[178:193]
	v_mfma_f32_32x32x16_bf16 v[162:177], v[110:113], v[80:83], v[162:177]
	v_mfma_f32_32x32x16_bf16 v[178:193], v[126:129], v[80:83], v[178:193]
	s_add_u32 s22, s18, 0x2000
	s_addc_u32 s23, s19, 0
	global_load_dwordx4 v[98:101], v194, s[22:23]
	global_load_dwordx4 v[102:105], v194, s[22:23] offset:1024
	global_load_dwordx4 v[106:109], v194, s[22:23] offset:2048
	global_load_dwordx4 v[110:113], v194, s[22:23] offset:3072
	global_load_dwordx4 v[114:117], v200, s[22:23]
	global_load_dwordx4 v[118:121], v202, s[22:23]
	global_load_dwordx4 v[122:125], v204, s[22:23]
	global_load_dwordx4 v[126:129], v206, s[22:23]
	v_sub_u32_e32 v239, v211, v226
	s_nop 0
	v_fmamk_f32 v162, v162, 0x3fb8aa3b, v208
	v_cmp_gt_u32_e32 vcc, 512, v239
	s_nop 1
	v_cndmask_b32_e32 v162, v219, v162, vcc
	v_fmamk_f32 v163, v163, 0x3fb8aa3b, v208
	v_cmp_gt_u32_e32 vcc, 513, v239
	s_nop 1
	v_cndmask_b32_e32 v163, v219, v163, vcc
	v_fmamk_f32 v164, v164, 0x3fb8aa3b, v208
	v_cmp_gt_u32_e32 vcc, 514, v239
	s_nop 1
	v_cndmask_b32_e32 v164, v219, v164, vcc
	v_fmamk_f32 v165, v165, 0x3fb8aa3b, v208
	v_cmp_gt_u32_e32 vcc, 515, v239
	s_nop 1
	v_cndmask_b32_e32 v165, v219, v165, vcc
	v_fmamk_f32 v166, v166, 0x3fb8aa3b, v208
	v_cmp_gt_u32_e32 vcc, 520, v239
	s_nop 1
	v_cndmask_b32_e32 v166, v219, v166, vcc
	v_fmamk_f32 v167, v167, 0x3fb8aa3b, v208
	v_cmp_gt_u32_e32 vcc, 521, v239
	s_nop 1
	v_cndmask_b32_e32 v167, v219, v167, vcc
	v_fmamk_f32 v168, v168, 0x3fb8aa3b, v208
	v_cmp_gt_u32_e32 vcc, 522, v239
	s_nop 1
	v_cndmask_b32_e32 v168, v219, v168, vcc
	v_fmamk_f32 v169, v169, 0x3fb8aa3b, v208
	v_cmp_gt_u32_e32 vcc, 523, v239
	s_nop 1
	v_cndmask_b32_e32 v169, v219, v169, vcc
	v_fmamk_f32 v170, v170, 0x3fb8aa3b, v208
	v_cmp_gt_u32_e32 vcc, 528, v239
	s_nop 1
	v_cndmask_b32_e32 v170, v219, v170, vcc
	v_fmamk_f32 v171, v171, 0x3fb8aa3b, v208
	v_cmp_gt_u32_e32 vcc, 529, v239
	s_nop 1
	v_cndmask_b32_e32 v171, v219, v171, vcc
	v_fmamk_f32 v172, v172, 0x3fb8aa3b, v208
	v_cmp_gt_u32_e32 vcc, 530, v239
	s_nop 1
	v_cndmask_b32_e32 v172, v219, v172, vcc
	v_fmamk_f32 v173, v173, 0x3fb8aa3b, v208
	v_cmp_gt_u32_e32 vcc, 531, v239
	s_nop 1
	v_cndmask_b32_e32 v173, v219, v173, vcc
	v_fmamk_f32 v174, v174, 0x3fb8aa3b, v208
	v_cmp_gt_u32_e32 vcc, 536, v239
	s_nop 1
	v_cndmask_b32_e32 v174, v219, v174, vcc
	v_fmamk_f32 v175, v175, 0x3fb8aa3b, v208
	v_cmp_gt_u32_e32 vcc, 537, v239
	s_nop 1
	v_cndmask_b32_e32 v175, v219, v175, vcc
	v_fmamk_f32 v176, v176, 0x3fb8aa3b, v208
	v_cmp_gt_u32_e32 vcc, 538, v239
	s_nop 1
	v_cndmask_b32_e32 v176, v219, v176, vcc
	v_fmamk_f32 v177, v177, 0x3fb8aa3b, v208
	v_cmp_gt_u32_e32 vcc, 539, v239
	s_nop 1
	v_cndmask_b32_e32 v177, v219, v177, vcc
	v_fmamk_f32 v178, v178, 0x3fb8aa3b, v208
	v_cmp_gt_u32_e32 vcc, 544, v239
	s_nop 1
	v_cndmask_b32_e32 v178, v219, v178, vcc
	v_fmamk_f32 v179, v179, 0x3fb8aa3b, v208
	v_cmp_gt_u32_e32 vcc, 545, v239
	s_nop 1
	v_cndmask_b32_e32 v179, v219, v179, vcc
	v_fmamk_f32 v180, v180, 0x3fb8aa3b, v208
	v_cmp_gt_u32_e32 vcc, 546, v239
	s_nop 1
	v_cndmask_b32_e32 v180, v219, v180, vcc
	v_fmamk_f32 v181, v181, 0x3fb8aa3b, v208
	v_cmp_gt_u32_e32 vcc, 547, v239
	s_nop 1
	v_cndmask_b32_e32 v181, v219, v181, vcc
	v_fmamk_f32 v182, v182, 0x3fb8aa3b, v208
	v_cmp_gt_u32_e32 vcc, 552, v239
	s_nop 1
	v_cndmask_b32_e32 v182, v219, v182, vcc
	v_fmamk_f32 v183, v183, 0x3fb8aa3b, v208
	v_cmp_gt_u32_e32 vcc, 553, v239
	s_nop 1
	v_cndmask_b32_e32 v183, v219, v183, vcc
	v_fmamk_f32 v184, v184, 0x3fb8aa3b, v208
	v_cmp_gt_u32_e32 vcc, 554, v239
	s_nop 1
	v_cndmask_b32_e32 v184, v219, v184, vcc
	v_fmamk_f32 v185, v185, 0x3fb8aa3b, v208
	v_cmp_gt_u32_e32 vcc, 555, v239
	s_nop 1
	v_cndmask_b32_e32 v185, v219, v185, vcc
	v_fmamk_f32 v186, v186, 0x3fb8aa3b, v208
	v_cmp_gt_u32_e32 vcc, 560, v239
	s_nop 1
	v_cndmask_b32_e32 v186, v219, v186, vcc
	v_fmamk_f32 v187, v187, 0x3fb8aa3b, v208
	v_cmp_gt_u32_e32 vcc, 561, v239
	s_nop 1
	v_cndmask_b32_e32 v187, v219, v187, vcc
	v_fmamk_f32 v188, v188, 0x3fb8aa3b, v208
	v_cmp_gt_u32_e32 vcc, 562, v239
	s_nop 1
	v_cndmask_b32_e32 v188, v219, v188, vcc
	v_fmamk_f32 v189, v189, 0x3fb8aa3b, v208
	v_cmp_gt_u32_e32 vcc, 563, v239
	s_nop 1
	v_cndmask_b32_e32 v189, v219, v189, vcc
	v_fmamk_f32 v190, v190, 0x3fb8aa3b, v208
	v_cmp_gt_u32_e32 vcc, 568, v239
	s_nop 1
	v_cndmask_b32_e32 v190, v219, v190, vcc
	v_fmamk_f32 v191, v191, 0x3fb8aa3b, v208
	v_cmp_gt_u32_e32 vcc, 569, v239
	s_nop 1
	v_cndmask_b32_e32 v191, v219, v191, vcc
	v_fmamk_f32 v192, v192, 0x3fb8aa3b, v208
	v_cmp_gt_u32_e32 vcc, 570, v239
	s_nop 1
	v_cndmask_b32_e32 v192, v219, v192, vcc
	v_fmamk_f32 v193, v193, 0x3fb8aa3b, v208
	v_cmp_gt_u32_e32 vcc, 571, v239
	s_nop 1
	v_cndmask_b32_e32 v193, v219, v193, vcc
	v_max3_f32 v92, v162, v163, v164
	v_max3_f32 v92, v92, v165, v166
	v_max3_f32 v92, v92, v167, v168
	v_max3_f32 v92, v92, v169, v170
	v_max3_f32 v92, v92, v171, v172
	v_max3_f32 v92, v92, v173, v174
	v_max3_f32 v92, v92, v175, v176
	v_max3_f32 v92, v92, v177, v177
	v_max3_f32 v97, v178, v179, v180
	v_max3_f32 v97, v97, v181, v182
	v_max3_f32 v97, v97, v183, v184
	v_max3_f32 v97, v97, v185, v186
	v_max3_f32 v97, v97, v187, v188
	v_max3_f32 v97, v97, v189, v190
	v_max3_f32 v97, v97, v191, v192
	v_max3_f32 v97, v97, v193, v193
	v_max_f32_e32 v92, v92, v97
	v_mov_b32_e32 v93, v92
	s_nop 1
	v_permlane32_swap_b32_e32 v92, v93
	v_max3_f32 v97, v234, v92, v93
	v_cmp_neq_f32_e32 vcc, s68, v97
	s_nop 1
	v_cndmask_b32_e32 v94, 0, v97, vcc
	v_cmp_neq_f32_e32 vcc, v97, v234
	s_cbranch_vccz .Lw_nr_band
	v_sub_f32_e32 v96, v234, v94
	v_exp_f32_e32 v96, v96
	s_nop 0
	v_pk_mul_f32 v[34:35], v[34:35], v[96:97] op_sel_hi:[1,0]
	v_pk_mul_f32 v[36:37], v[36:37], v[96:97] op_sel_hi:[1,0]
	v_pk_mul_f32 v[38:39], v[38:39], v[96:97] op_sel_hi:[1,0]
	v_pk_mul_f32 v[40:41], v[40:41], v[96:97] op_sel_hi:[1,0]
	v_pk_mul_f32 v[42:43], v[42:43], v[96:97] op_sel_hi:[1,0]
	v_pk_mul_f32 v[44:45], v[44:45], v[96:97] op_sel_hi:[1,0]
	v_pk_mul_f32 v[46:47], v[46:47], v[96:97] op_sel_hi:[1,0]
	v_pk_mul_f32 v[48:49], v[48:49], v[96:97] op_sel_hi:[1,0]
	v_pk_mul_f32 v[50:51], v[50:51], v[96:97] op_sel_hi:[1,0]
	v_pk_mul_f32 v[52:53], v[52:53], v[96:97] op_sel_hi:[1,0]
	v_pk_mul_f32 v[54:55], v[54:55], v[96:97] op_sel_hi:[1,0]
	v_pk_mul_f32 v[56:57], v[56:57], v[96:97] op_sel_hi:[1,0]
	v_pk_mul_f32 v[58:59], v[58:59], v[96:97] op_sel_hi:[1,0]
	v_pk_mul_f32 v[60:61], v[60:61], v[96:97] op_sel_hi:[1,0]
	v_pk_mul_f32 v[62:63], v[62:63], v[96:97] op_sel_hi:[1,0]
	v_pk_mul_f32 v[64:65], v[64:65], v[96:97] op_sel_hi:[1,0]
	v_mul_f32_e32 v66, v96, v66
.Lw_nr_band:
	v_mov_b32_e32 v234, v97
	v_pk_add_f32 v[162:163], v[162:163], v[94:95] op_sel_hi:[1,0] neg_lo:[0,1] neg_hi:[0,1]
	v_pk_add_f32 v[164:165], v[164:165], v[94:95] op_sel_hi:[1,0] neg_lo:[0,1] neg_hi:[0,1]
	v_pk_add_f32 v[166:167], v[166:167], v[94:95] op_sel_hi:[1,0] neg_lo:[0,1] neg_hi:[0,1]
	v_pk_add_f32 v[168:169], v[168:169], v[94:95] op_sel_hi:[1,0] neg_lo:[0,1] neg_hi:[0,1]
	v_exp_f32_e32 v162, v162
	v_exp_f32_e32 v163, v163
	v_exp_f32_e32 v164, v164
	v_exp_f32_e32 v165, v165
	v_exp_f32_e32 v166, v166
	v_exp_f32_e32 v167, v167
	v_exp_f32_e32 v168, v168
	v_exp_f32_e32 v169, v169
	v_pk_add_f32 v[236:237], v[162:163], v[164:165]
	v_pk_add_f32 v[236:237], v[236:237], v[166:167]
	v_pk_add_f32 v[236:237], v[236:237], v[168:169]
	v_cvt_pk_bf16_f32 v84, v162, v163
	v_cvt_pk_bf16_f32 v85, v164, v165
	v_cvt_pk_bf16_f32 v86, v166, v167
	v_cvt_pk_bf16_f32 v87, v168, v169
	v_pk_add_f32 v[170:171], v[170:171], v[94:95] op_sel_hi:[1,0] neg_lo:[0,1] neg_hi:[0,1]
	v_pk_add_f32 v[172:173], v[172:173], v[94:95] op_sel_hi:[1,0] neg_lo:[0,1] neg_hi:[0,1]
	v_pk_add_f32 v[174:175], v[174:175], v[94:95] op_sel_hi:[1,0] neg_lo:[0,1] neg_hi:[0,1]
	v_pk_add_f32 v[176:177], v[176:177], v[94:95] op_sel_hi:[1,0] neg_lo:[0,1] neg_hi:[0,1]
	s_waitcnt vmcnt(8)
	v_mfma_f32_32x32x16_bf16 v[34:49], v[130:133], v[84:87], v[34:49]
	v_mfma_f32_32x32x16_bf16 v[50:65], v[146:149], v[84:87], v[50:65]
	v_exp_f32_e32 v170, v170
	v_exp_f32_e32 v171, v171
	v_exp_f32_e32 v172, v172
	v_exp_f32_e32 v173, v173
	v_exp_f32_e32 v174, v174
	v_exp_f32_e32 v175, v175
	v_exp_f32_e32 v176, v176
	v_exp_f32_e32 v177, v177
	v_pk_add_f32 v[236:237], v[236:237], v[170:171]
	v_pk_add_f32 v[236:237], v[236:237], v[172:173]
	v_pk_add_f32 v[236:237], v[236:237], v[174:175]
	v_pk_add_f32 v[236:237], v[236:237], v[176:177]
	v_cvt_pk_bf16_f32 v88, v170, v171
	v_cvt_pk_bf16_f32 v89, v172, v173
	v_cvt_pk_bf16_f32 v90, v174, v175
	v_cvt_pk_bf16_f32 v91, v176, v177
	v_pk_add_f32 v[178:179], v[178:179], v[94:95] op_sel_hi:[1,0] neg_lo:[0,1] neg_hi:[0,1]
	v_pk_add_f32 v[180:181], v[180:181], v[94:95] op_sel_hi:[1,0] neg_lo:[0,1] neg_hi:[0,1]
	v_pk_add_f32 v[182:183], v[182:183], v[94:95] op_sel_hi:[1,0] neg_lo:[0,1] neg_hi:[0,1]
	v_pk_add_f32 v[184:185], v[184:185], v[94:95] op_sel_hi:[1,0] neg_lo:[0,1] neg_hi:[0,1]
	v_mfma_f32_32x32x16_bf16 v[34:49], v[134:137], v[88:91], v[34:49]
	v_mfma_f32_32x32x16_bf16 v[50:65], v[150:153], v[88:91], v[50:65]
	v_exp_f32_e32 v178, v178
	v_exp_f32_e32 v179, v179
	v_exp_f32_e32 v180, v180
	v_exp_f32_e32 v181, v181
	v_exp_f32_e32 v182, v182
	v_exp_f32_e32 v183, v183
	v_exp_f32_e32 v184, v184
	v_exp_f32_e32 v185, v185
	v_pk_add_f32 v[236:237], v[236:237], v[178:179]
	v_pk_add_f32 v[236:237], v[236:237], v[180:181]
	v_pk_add_f32 v[236:237], v[236:237], v[182:183]
	v_pk_add_f32 v[236:237], v[236:237], v[184:185]
	v_cvt_pk_bf16_f32 v84, v178, v179
	v_cvt_pk_bf16_f32 v85, v180, v181
	v_cvt_pk_bf16_f32 v86, v182, v183
	v_cvt_pk_bf16_f32 v87, v184, v185
	v_pk_add_f32 v[186:187], v[186:187], v[94:95] op_sel_hi:[1,0] neg_lo:[0,1] neg_hi:[0,1]
	v_pk_add_f32 v[188:189], v[188:189], v[94:95] op_sel_hi:[1,0] neg_lo:[0,1] neg_hi:[0,1]
	v_pk_add_f32 v[190:191], v[190:191], v[94:95] op_sel_hi:[1,0] neg_lo:[0,1] neg_hi:[0,1]
	v_pk_add_f32 v[192:193], v[192:193], v[94:95] op_sel_hi:[1,0] neg_lo:[0,1] neg_hi:[0,1]
	v_mfma_f32_32x32x16_bf16 v[34:49], v[138:141], v[84:87], v[34:49]
	v_mfma_f32_32x32x16_bf16 v[50:65], v[154:157], v[84:87], v[50:65]
	v_exp_f32_e32 v186, v186
	v_exp_f32_e32 v187, v187
	v_exp_f32_e32 v188, v188
	v_exp_f32_e32 v189, v189
	v_exp_f32_e32 v190, v190
	v_exp_f32_e32 v191, v191
	v_exp_f32_e32 v192, v192
	v_exp_f32_e32 v193, v193
	v_pk_add_f32 v[236:237], v[236:237], v[186:187]
	v_pk_add_f32 v[236:237], v[236:237], v[188:189]
	v_pk_add_f32 v[236:237], v[236:237], v[190:191]
	v_pk_add_f32 v[236:237], v[236:237], v[192:193]
	v_cvt_pk_bf16_f32 v88, v186, v187
	v_cvt_pk_bf16_f32 v89, v188, v189
	v_cvt_pk_bf16_f32 v90, v190, v191
	v_cvt_pk_bf16_f32 v91, v192, v193
	s_nop 1
	v_mfma_f32_32x32x16_bf16 v[34:49], v[142:145], v[88:91], v[34:49]
	v_mfma_f32_32x32x16_bf16 v[50:65], v[158:161], v[88:91], v[50:65]
	v_add_f32_e32 v235, v236, v237
	v_add_f32_e32 v66, v66, v235
	s_branch .Lw_next
.Lw_near:
	v_sub_u32_e32 v240, v232, v226
	v_lshl_add_u32 v240, v240, 2, v225
	s_waitcnt vmcnt(8)
	v_mfma_f32_32x32x16_bf16 v[162:177], v[98:101], v[68:71], 0
	v_mfma_f32_32x32x16_bf16 v[178:193], v[114:117], v[68:71], 0
	v_mfma_f32_32x32x16_bf16 v[162:177], v[102:105], v[72:75], v[162:177]
	v_mfma_f32_32x32x16_bf16 v[178:193], v[118:121], v[72:75], v[178:193]
	v_mfma_f32_32x32x16_bf16 v[162:177], v[106:109], v[76:79], v[162:177]
	v_mfma_f32_32x32x16_bf16 v[178:193], v[122:125], v[76:79], v[178:193]
	v_mfma_f32_32x32x16_bf16 v[162:177], v[110:113], v[80:83], v[162:177]
	v_mfma_f32_32x32x16_bf16 v[178:193], v[126:129], v[80:83], v[178:193]
	ds_read2_b32 v[2:3], v240 offset0:64 offset1:63
	ds_read2_b32 v[4:5], v240 offset0:62 offset1:61
	ds_read2_b32 v[6:7], v240 offset0:56 offset1:55
	ds_read2_b32 v[8:9], v240 offset0:54 offset1:53
	ds_read2_b32 v[10:11], v240 offset0:48 offset1:47
	ds_read2_b32 v[12:13], v240 offset0:46 offset1:45
	ds_read2_b32 v[14:15], v240 offset0:40 offset1:39
	ds_read2_b32 v[16:17], v240 offset0:38 offset1:37
	ds_read2_b32 v[18:19], v240 offset0:32 offset1:31
	ds_read2_b32 v[20:21], v240 offset0:30 offset1:29
	ds_read2_b32 v[22:23], v240 offset0:24 offset1:23
	ds_read2_b32 v[24:25], v240 offset0:22 offset1:21
	ds_read2_b32 v[26:27], v240 offset0:16 offset1:15
	ds_read2_b32 v[28:29], v240 offset0:14 offset1:13
	ds_read2_b32 v[30:31], v240 offset0:8 offset1:7
	ds_read2_b32 v[32:33], v240 offset0:6 offset1:5
	s_cmp_lt_i32 s17, s44
	s_cbranch_scc0 .Lw_near_last
	s_add_u32 s22, s18, 0x2000
	s_addc_u32 s23, s19, 0
	global_load_dwordx4 v[98:101], v194, s[22:23]
	global_load_dwordx4 v[102:105], v194, s[22:23] offset:1024
	global_load_dwordx4 v[106:109], v194, s[22:23] offset:2048
	global_load_dwordx4 v[110:113], v194, s[22:23] offset:3072
	global_load_dwordx4 v[114:117], v200, s[22:23]
	global_load_dwordx4 v[118:121], v202, s[22:23]
	global_load_dwordx4 v[122:125], v204, s[22:23]
	global_load_dwordx4 v[126:129], v206, s[22:23]
.Lw_near_last:
	s_waitcnt lgkmcnt(8)
	v_pk_fma_f32 v[162:163], v[162:163], v[242:243], v[2:3] op_sel_hi:[1,0,1]
	v_pk_fma_f32 v[164:165], v[164:165], v[242:243], v[4:5] op_sel_hi:[1,0,1]
	v_pk_fma_f32 v[166:167], v[166:167], v[242:243], v[6:7] op_sel_hi:[1,0,1]
	v_pk_fma_f32 v[168:169], v[168:169], v[242:243], v[8:9] op_sel_hi:[1,0,1]
	v_pk_fma_f32 v[170:171], v[170:171], v[242:243], v[10:11] op_sel_hi:[1,0,1]
	v_pk_fma_f32 v[172:173], v[172:173], v[242:243], v[12:13] op_sel_hi:[1,0,1]
	v_pk_fma_f32 v[174:175], v[174:175], v[242:243], v[14:15] op_sel_hi:[1,0,1]
	v_pk_fma_f32 v[176:177], v[176:177], v[242:243], v[16:17] op_sel_hi:[1,0,1]
	s_waitcnt lgkmcnt(0)
	v_pk_fma_f32 v[178:179], v[178:179], v[242:243], v[18:19] op_sel_hi:[1,0,1]
	v_pk_fma_f32 v[180:181], v[180:181], v[242:243], v[20:21] op_sel_hi:[1,0,1]
	v_pk_fma_f32 v[182:183], v[182:183], v[242:243], v[22:23] op_sel_hi:[1,0,1]
	v_pk_fma_f32 v[184:185], v[184:185], v[242:243], v[24:25] op_sel_hi:[1,0,1]
	v_pk_fma_f32 v[186:187], v[186:187], v[242:243], v[26:27] op_sel_hi:[1,0,1]
	v_pk_fma_f32 v[188:189], v[188:189], v[242:243], v[28:29] op_sel_hi:[1,0,1]
	v_pk_fma_f32 v[190:191], v[190:191], v[242:243], v[30:31] op_sel_hi:[1,0,1]
	v_pk_fma_f32 v[192:193], v[192:193], v[242:243], v[32:33] op_sel_hi:[1,0,1]
	v_max3_f32 v92, v162, v163, v164
	v_max3_f32 v92, v92, v165, v166
	v_max3_f32 v92, v92, v167, v168
	v_max3_f32 v92, v92, v169, v170
	v_max3_f32 v92, v92, v171, v172
	v_max3_f32 v92, v92, v173, v174
	v_max3_f32 v92, v92, v175, v176
	v_max3_f32 v92, v92, v177, v177
	v_max3_f32 v97, v178, v179, v180
	v_max3_f32 v97, v97, v181, v182
	v_max3_f32 v97, v97, v183, v184
	v_max3_f32 v97, v97, v185, v186
	v_max3_f32 v97, v97, v187, v188
	v_max3_f32 v97, v97, v189, v190
	v_max3_f32 v97, v97, v191, v192
	v_max3_f32 v97, v97, v193, v193
	v_max_f32_e32 v92, v92, v97
	v_mov_b32_e32 v93, v92
	s_nop 1
	v_permlane32_swap_b32_e32 v92, v93
	v_max3_f32 v97, v234, v92, v93
	v_cmp_neq_f32_e32 vcc, s68, v97
	s_nop 1
	v_cndmask_b32_e32 v94, 0, v97, vcc
	v_cmp_neq_f32_e32 vcc, v97, v234
	s_cbranch_vccz .Lw_nr_near
	v_sub_f32_e32 v96, v234, v94
	v_exp_f32_e32 v96, v96
	s_nop 0
	v_pk_mul_f32 v[34:35], v[34:35], v[96:97] op_sel_hi:[1,0]
	v_pk_mul_f32 v[36:37], v[36:37], v[96:97] op_sel_hi:[1,0]
	v_pk_mul_f32 v[38:39], v[38:39], v[96:97] op_sel_hi:[1,0]
	v_pk_mul_f32 v[40:41], v[40:41], v[96:97] op_sel_hi:[1,0]
	v_pk_mul_f32 v[42:43], v[42:43], v[96:97] op_sel_hi:[1,0]
	v_pk_mul_f32 v[44:45], v[44:45], v[96:97] op_sel_hi:[1,0]
	v_pk_mul_f32 v[46:47], v[46:47], v[96:97] op_sel_hi:[1,0]
	v_pk_mul_f32 v[48:49], v[48:49], v[96:97] op_sel_hi:[1,0]
	v_pk_mul_f32 v[50:51], v[50:51], v[96:97] op_sel_hi:[1,0]
	v_pk_mul_f32 v[52:53], v[52:53], v[96:97] op_sel_hi:[1,0]
	v_pk_mul_f32 v[54:55], v[54:55], v[96:97] op_sel_hi:[1,0]
	v_pk_mul_f32 v[56:57], v[56:57], v[96:97] op_sel_hi:[1,0]
	v_pk_mul_f32 v[58:59], v[58:59], v[96:97] op_sel_hi:[1,0]
	v_pk_mul_f32 v[60:61], v[60:61], v[96:97] op_sel_hi:[1,0]
	v_pk_mul_f32 v[62:63], v[62:63], v[96:97] op_sel_hi:[1,0]
	v_pk_mul_f32 v[64:65], v[64:65], v[96:97] op_sel_hi:[1,0]
	v_mul_f32_e32 v66, v96, v66
.Lw_nr_near:
	v_mov_b32_e32 v234, v97
	v_pk_add_f32 v[162:163], v[162:163], v[94:95] op_sel_hi:[1,0] neg_lo:[0,1] neg_hi:[0,1]
	v_pk_add_f32 v[164:165], v[164:165], v[94:95] op_sel_hi:[1,0] neg_lo:[0,1] neg_hi:[0,1]
	v_pk_add_f32 v[166:167], v[166:167], v[94:95] op_sel_hi:[1,0] neg_lo:[0,1] neg_hi:[0,1]
	v_pk_add_f32 v[168:169], v[168:169], v[94:95] op_sel_hi:[1,0] neg_lo:[0,1] neg_hi:[0,1]
	v_exp_f32_e32 v162, v162
	v_exp_f32_e32 v163, v163
	v_exp_f32_e32 v164, v164
	v_exp_f32_e32 v165, v165
	v_exp_f32_e32 v166, v166
	v_exp_f32_e32 v167, v167
	v_exp_f32_e32 v168, v168
	v_exp_f32_e32 v169, v169
	v_pk_add_f32 v[236:237], v[162:163], v[164:165]
	v_pk_add_f32 v[236:237], v[236:237], v[166:167]
	v_pk_add_f32 v[236:237], v[236:237], v[168:169]
	v_cvt_pk_bf16_f32 v84, v162, v163
	v_cvt_pk_bf16_f32 v85, v164, v165
	v_cvt_pk_bf16_f32 v86, v166, v167
	v_cvt_pk_bf16_f32 v87, v168, v169
	v_pk_add_f32 v[170:171], v[170:171], v[94:95] op_sel_hi:[1,0] neg_lo:[0,1] neg_hi:[0,1]
	v_pk_add_f32 v[172:173], v[172:173], v[94:95] op_sel_hi:[1,0] neg_lo:[0,1] neg_hi:[0,1]
	v_pk_add_f32 v[174:175], v[174:175], v[94:95] op_sel_hi:[1,0] neg_lo:[0,1] neg_hi:[0,1]
	v_pk_add_f32 v[176:177], v[176:177], v[94:95] op_sel_hi:[1,0] neg_lo:[0,1] neg_hi:[0,1]
	s_cmp_lt_i32 s17, s44
	s_cbranch_scc1 .Lw_near_w8
	s_waitcnt vmcnt(0)
	s_branch .Lw_near_pv

.Lw_near_pv:
	v_mfma_f32_32x32x16_bf16 v[34:49], v[130:133], v[84:87], v[34:49]
	v_mfma_f32_32x32x16_bf16 v[50:65], v[146:149], v[84:87], v[50:65]
	v_exp_f32_e32 v170, v170
	v_exp_f32_e32 v171, v171
	v_exp_f32_e32 v172, v172
	v_exp_f32_e32 v173, v173
	v_exp_f32_e32 v174, v174
	v_exp_f32_e32 v175, v175
	v_exp_f32_e32 v176, v176
	v_exp_f32_e32 v177, v177
	v_pk_add_f32 v[236:237], v[236:237], v[170:171]
	v_pk_add_f32 v[236:237], v[236:237], v[172:173]
	v_pk_add_f32 v[236:237], v[236:237], v[174:175]
	v_pk_add_f32 v[236:237], v[236:237], v[176:177]
	v_cvt_pk_bf16_f32 v88, v170, v171
	v_cvt_pk_bf16_f32 v89, v172, v173
	v_cvt_pk_bf16_f32 v90, v174, v175
	v_cvt_pk_bf16_f32 v91, v176, v177
	v_pk_add_f32 v[178:179], v[178:179], v[94:95] op_sel_hi:[1,0] neg_lo:[0,1] neg_hi:[0,1]
	v_pk_add_f32 v[180:181], v[180:181], v[94:95] op_sel_hi:[1,0] neg_lo:[0,1] neg_hi:[0,1]
	v_pk_add_f32 v[182:183], v[182:183], v[94:95] op_sel_hi:[1,0] neg_lo:[0,1] neg_hi:[0,1]
	v_pk_add_f32 v[184:185], v[184:185], v[94:95] op_sel_hi:[1,0] neg_lo:[0,1] neg_hi:[0,1]
	v_mfma_f32_32x32x16_bf16 v[34:49], v[134:137], v[88:91], v[34:49]
	v_mfma_f32_32x32x16_bf16 v[50:65], v[150:153], v[88:91], v[50:65]
	v_exp_f32_e32 v178, v178
	v_exp_f32_e32 v179, v179
	v_exp_f32_e32 v180, v180
	v_exp_f32_e32 v181, v181
	v_exp_f32_e32 v182, v182
	v_exp_f32_e32 v183, v183
	v_exp_f32_e32 v184, v184
	v_exp_f32_e32 v185, v185
	v_pk_add_f32 v[236:237], v[236:237], v[178:179]
	v_pk_add_f32 v[236:237], v[236:237], v[180:181]
	v_pk_add_f32 v[236:237], v[236:237], v[182:183]
	v_pk_add_f32 v[236:237], v[236:237], v[184:185]
	v_cvt_pk_bf16_f32 v84, v178, v179
	v_cvt_pk_bf16_f32 v85, v180, v181
	v_cvt_pk_bf16_f32 v86, v182, v183
	v_cvt_pk_bf16_f32 v87, v184, v185
	v_pk_add_f32 v[186:187], v[186:187], v[94:95] op_sel_hi:[1,0] neg_lo:[0,1] neg_hi:[0,1]
	v_pk_add_f32 v[188:189], v[188:189], v[94:95] op_sel_hi:[1,0] neg_lo:[0,1] neg_hi:[0,1]
	v_pk_add_f32 v[190:191], v[190:191], v[94:95] op_sel_hi:[1,0] neg_lo:[0,1] neg_hi:[0,1]
	v_pk_add_f32 v[192:193], v[192:193], v[94:95] op_sel_hi:[1,0] neg_lo:[0,1] neg_hi:[0,1]
	v_mfma_f32_32x32x16_bf16 v[34:49], v[138:141], v[84:87], v[34:49]
	v_mfma_f32_32x32x16_bf16 v[50:65], v[154:157], v[84:87], v[50:65]
	v_exp_f32_e32 v186, v186
	v_exp_f32_e32 v187, v187
	v_exp_f32_e32 v188, v188
	v_exp_f32_e32 v189, v189
	v_exp_f32_e32 v190, v190
	v_exp_f32_e32 v191, v191
	v_exp_f32_e32 v192, v192
	v_exp_f32_e32 v193, v193
	v_pk_add_f32 v[236:237], v[236:237], v[186:187]
	v_pk_add_f32 v[236:237], v[236:237], v[188:189]
	v_pk_add_f32 v[236:237], v[236:237], v[190:191]
	v_pk_add_f32 v[236:237], v[236:237], v[192:193]
	v_cvt_pk_bf16_f32 v88, v186, v187
	v_cvt_pk_bf16_f32 v89, v188, v189
	v_cvt_pk_bf16_f32 v90, v190, v191
	v_cvt_pk_bf16_f32 v91, v192, v193
	s_nop 1
	v_mfma_f32_32x32x16_bf16 v[34:49], v[142:145], v[88:91], v[34:49]
	v_mfma_f32_32x32x16_bf16 v[50:65], v[158:161], v[88:91], v[50:65]
	v_add_f32_e32 v235, v236, v237
	v_add_f32_e32 v66, v66, v235
